# P7 head: wave-0 gate loads issued ahead of the C^T fragment loads and waited with vmcnt(16)
# baseline (speedup 1.0000x reference)
; DI void mlstm_out_unit(const Params& p, unsigned char* smem, const int tid, int u) {
;     ...
;     const float mc = ((const float*)(ws + OFF_MST))[bh * 132 + c];
;     const size_t tok0 = (size_t)bh * 8192 + c * 64;
;     bf16x8 ctf[4][4];
;     {
;         const int i16 = lane & 15;
;         const bf16_t* ctb0 = CT + (((size_t)bh * 128 + c) * 256 + 64 * w + (i16 >> 2) * 8 + (i16 & 3)) * 128 + (lane >> 4) * 8;
; #pragma unroll
;         for (int ks = 0; ks < 4; ++ks)
; #pragma unroll
;             for (int i = 0; i < 4; ++i) ctf[ks][i] = ld16(ctb0 + (size_t)((i >> 1) * 32 + (i & 1) * 4) * 128 + ks * 32);
;     }
;     if (w == 0) {
;         float bj = ((const float*)(ws + OFF_BCUM))[tok0 + lane], ij = ((const float*)(ws + OFF_IG))[tok0 + lane];
;         float g = ij - bj, pm = g;
;         for (int d = 1; d < 64; d <<= 1) { float o = __shfl_up(pm, d, 64); if (lane >= d) pm = fmaxf(pm, o); }
;         float mt = bj + fmaxf(mc, pm);
;         gk[lane] = g; bq[lane] = bj - mt; sci[lane] = __expf(bj + mc - mt); emt[lane] = __expf(-mt);
;     }
.LBB0_717:
	v_ashrrev_i32_e32 v126, 7, v97
	v_ashrrev_i32_e32 v127, 31, v126
	v_and_b32_e32 v66, 0x7f, v97
	s_mov_b64 s[86:87], exec
	s_andn2_b64 exec, exec, s[56:57]
	s_cbranch_execz .Lp7g_a
	v_lshlrev_b32_e32 v204, 6, v66
	v_lshlrev_b64 v[206:207], 13, v[126:127]
	s_movk_i32 s88, 0x84
	v_mov_b32_e32 v208, v66
	v_mov_b32_e32 v209, 0
	v_or3_b32 v206, v206, v204, v96
	v_mad_u64_u32 v[208:209], vcc, v126, s88, v[208:209]
	v_readlane_b32 s4, v255, 0
	v_readlane_b32 s5, v255, 1
	v_ashrrev_i32_e32 v209, 31, v208
	v_lshlrev_b64 v[206:207], 2, v[206:207]
	v_lshl_add_u64 v[208:209], v[208:209], 2, s[94:95]
	global_load_dword v210, v[208:209], off
	v_lshl_add_u64 v[208:209], s[96:97], 0, v[206:207]
	v_lshl_add_u64 v[206:207], s[4:5], 0, v[206:207]
	global_load_dword v211, v[208:209], off
	global_load_dword v212, v[206:207], off
.Lp7g_a:
	s_mov_b64 exec, s[86:87]
	v_lshlrev_b64 v[64:65], 7, v[126:127]
	v_or_b32_e32 v64, v64, v66
	v_lshlrev_b64 v[128:129], 8, v[64:65]
	v_or_b32_e32 v128, v128, v98
	v_lshlrev_b64 v[0:1], 8, v[128:129]
	v_lshl_add_u64 v[0:1], v[102:103], 0, v[0:1]
	v_add_co_u32_e32 v2, vcc, s91, v0
	s_nop 1
	v_addc_co_u32_e32 v3, vcc, 0, v1, vcc
	global_load_dwordx4 v[52:55], v[0:1], off
	global_load_dwordx4 v[44:47], v[0:1], off offset:64
	global_load_dwordx4 v[60:63], v[0:1], off offset:1024
	global_load_dwordx4 v[40:43], v[0:1], off offset:1088
	global_load_dwordx4 v[56:59], v[2:3], off
	global_load_dwordx4 v[36:39], v[2:3], off offset:64
	global_load_dwordx4 v[48:51], v[2:3], off offset:1024
	global_load_dwordx4 v[32:35], v[2:3], off offset:1088
	global_load_dwordx4 v[24:27], v[0:1], off offset:128
	global_load_dwordx4 v[12:15], v[0:1], off offset:192
	global_load_dwordx4 v[28:31], v[0:1], off offset:1152
	global_load_dwordx4 v[8:11], v[0:1], off offset:1216
	global_load_dwordx4 v[20:23], v[2:3], off offset:128
	global_load_dwordx4 v[4:7], v[2:3], off offset:192
	global_load_dwordx4 v[16:19], v[2:3], off offset:1152
	s_nop 0
	global_load_dwordx4 v[0:3], v[2:3], off offset:1216
	s_and_saveexec_b64 s[86:87], s[56:57]
	s_xor_b64 s[86:87], exec, s[86:87]
	v_and_b32_e32 v77, 64, v138
	s_or_saveexec_b64 s[86:87], s[86:87]
	v_lshlrev_b32_e32 v139, 6, v66
	v_lshlrev_b64 v[72:73], 13, v[126:127]
	v_or_b32_e32 v76, v72, v139
	v_mov_b32_e32 v100, v138
	s_xor_b64 exec, exec, s[86:87]
	s_cbranch_execz .LBB0_721
	v_mbcnt_lo_u32_b32 v67, -1, 0
	v_mbcnt_hi_u32_b32 v100, -1, v67
	v_and_b32_e32 v77, 64, v100
	v_add_u32_e32 v67, -1, v100
	v_cmp_lt_i32_e32 vcc, v67, v77
	v_add_u32_e32 v69, -2, v100
	v_readlane_b32 s4, v254, 0
	v_cndmask_b32_e32 v67, v67, v100, vcc
	v_lshlrev_b32_e32 v67, 2, v67
	v_cmp_lt_i32_e32 vcc, v69, v77
	v_readlane_b32 s5, v254, 1
	s_waitcnt vmcnt(16)
	v_mov_b32_e32 v70, v210
	v_mov_b32_e32 v68, v211
	v_mov_b32_e32 v66, v212
	v_sub_f32_e32 v66, v66, v68
	ds_bpermute_b32 v67, v67, v66
	v_cndmask_b32_e32 v69, v69, v100, vcc
	v_lshlrev_b32_e32 v69, 2, v69
	s_waitcnt lgkmcnt(0)
	v_max_f32_e32 v67, v67, v67
	v_max_f32_e32 v67, v66, v67
	v_cndmask_b32_e64 v67, v67, v66, s[4:5]
	ds_bpermute_b32 v69, v69, v67
	s_waitcnt lgkmcnt(0)
	v_max_f32_e32 v69, v69, v69
	v_max_f32_e32 v69, v67, v69
	v_cndmask_b32_e64 v67, v69, v67, s[6:7]
	v_add_u32_e32 v69, -4, v100
	v_cmp_lt_i32_e32 vcc, v69, v77
	s_nop 1
	v_cndmask_b32_e32 v69, v69, v100, vcc
	v_lshlrev_b32_e32 v69, 2, v69
	ds_bpermute_b32 v69, v69, v67
	s_waitcnt lgkmcnt(0)
	v_max_f32_e32 v69, v69, v69
	v_max_f32_e32 v69, v67, v69
	v_cndmask_b32_e64 v67, v69, v67, s[8:9]
	v_add_u32_e32 v69, -8, v100
	v_cmp_lt_i32_e32 vcc, v69, v77
	s_nop 1
	v_cndmask_b32_e32 v69, v69, v100, vcc
	v_lshlrev_b32_e32 v69, 2, v69
	ds_bpermute_b32 v69, v69, v67
	s_waitcnt lgkmcnt(0)
	v_max_f32_e32 v69, v69, v69
	v_max_f32_e32 v69, v67, v69
	v_cndmask_b32_e64 v67, v69, v67, s[10:11]
	v_add_u32_e32 v69, -16, v100
	v_cmp_lt_i32_e32 vcc, v69, v77
	s_nop 1
	v_cndmask_b32_e32 v69, v69, v100, vcc
	v_lshlrev_b32_e32 v69, 2, v69
	ds_bpermute_b32 v69, v69, v67
	s_waitcnt lgkmcnt(0)
	v_max_f32_e32 v69, v69, v69
	v_max_f32_e32 v69, v67, v69
	v_cndmask_b32_e64 v67, v69, v67, s[12:13]
	v_subrev_u32_e32 v69, 32, v100
	v_cmp_lt_i32_e32 vcc, v69, v77
	v_max_f32_e32 v71, v67, v67
	s_nop 0
	v_cndmask_b32_e32 v69, v69, v100, vcc
	v_lshlrev_b32_e32 v69, 2, v69
	ds_bpermute_b32 v69, v69, v67
	s_waitcnt lgkmcnt(0)
	v_max_f32_e32 v69, v69, v69
	v_max_f32_e32 v69, v71, v69
	v_cndmask_b32_e64 v67, v69, v67, s[14:15]
	v_max_f32_e32 v67, v67, v67
	v_max_f32_e32 v69, v70, v70
	v_max_f32_e32 v67, v69, v67
	v_add_f32_e32 v67, v68, v67
	v_sub_f32_e32 v69, v68, v67
	ds_write2st64_b32 v99, v66, v69 offset1:1
	v_add_f32_e32 v66, v70, v68
	v_sub_f32_e32 v66, v66, v67
	v_mul_f32_e32 v66, 0x3fb8aa3b, v66
	v_mul_f32_e32 v67, 0xbfb8aa3b, v67
	v_exp_f32_e32 v66, v66
	v_exp_f32_e32 v67, v67
	ds_write2st64_b32 v99, v66, v67 offset0:2 offset1:3
